# gate/up GLU epilogue list-scheduled: silu exp/rcp temporaries renamed to free VGPRs so the 32 chains interleave
# baseline (speedup 1.0000x reference)
.LBB0_1605:
	s_waitcnt lgkmcnt(0)
	v_pk_mul_f32 v[126:127], v[126:127], v[0:1] op_sel_hi:[1,0]
	v_pk_mul_f32 v[134:135], v[134:135], v[0:1] op_sel_hi:[1,0]
	v_pk_mul_f32 v[118:119], v[118:119], v[0:1] op_sel:[0,1]
	v_pk_mul_f32 v[216:217], v[126:127], s[22:23] op_sel_hi:[1,0]
	v_pk_mul_f32 v[110:111], v[110:111], v[0:1] op_sel:[0,1]
	v_pk_mul_f32 v[212:213], v[134:135], s[22:23] op_sel_hi:[1,0]
	v_exp_f32_e32 v216, v216
	v_exp_f32_e32 v217, v217
	v_pk_mul_f32 v[218:219], v[118:119], s[22:23] op_sel_hi:[1,0]
	v_pk_mul_f32 v[222:223], v[110:111], s[22:23] op_sel_hi:[1,0]
	v_exp_f32_e32 v212, v212
	v_exp_f32_e32 v213, v213
	v_pk_add_f32 v[216:217], v[216:217], 1.0 op_sel_hi:[1,0]
	v_exp_f32_e32 v218, v218
	v_exp_f32_e32 v219, v219
	v_exp_f32_e32 v222, v222
	v_exp_f32_e32 v223, v223
	v_rcp_f32_e32 v216, v216
	v_rcp_f32_e32 v217, v217
	v_pk_add_f32 v[212:213], v[212:213], 1.0 op_sel_hi:[1,0]
	v_pk_add_f32 v[218:219], v[218:219], 1.0 op_sel_hi:[1,0]
	v_pk_add_f32 v[222:223], v[222:223], 1.0 op_sel_hi:[1,0]
	v_pk_mul_f32 v[122:123], v[122:123], v[0:1] op_sel_hi:[1,0]
	v_rcp_f32_e32 v212, v212
	v_rcp_f32_e32 v213, v213
	v_pk_mul_f32 v[126:127], v[126:127], v[216:217]
	v_rcp_f32_e32 v218, v218
	v_rcp_f32_e32 v219, v219
	v_rcp_f32_e32 v222, v222
	v_rcp_f32_e32 v223, v223
	v_pk_mul_f32 v[122:123], v[122:123], v[126:127]
	v_pk_mul_f32 v[130:131], v[130:131], v[0:1] op_sel_hi:[1,0]
	v_pk_mul_f32 v[114:115], v[114:115], v[0:1] op_sel:[0,1]
	v_pk_mul_f32 v[134:135], v[134:135], v[212:213]
	v_pk_mul_f32 v[106:107], v[106:107], v[0:1] op_sel:[0,1]
	v_pk_mul_f32 v[126:127], v[128:129], v[0:1] op_sel_hi:[1,0]
	v_pk_mul_f32 v[118:119], v[118:119], v[218:219]
	v_pk_mul_f32 v[110:111], v[110:111], v[222:223]
	v_pk_mul_f32 v[130:131], v[130:131], v[134:135]
	v_pk_mul_f32 v[128:129], v[126:127], s[22:23] op_sel_hi:[1,0]
	v_pk_mul_f32 v[114:115], v[114:115], v[118:119]
	v_pk_mul_f32 v[110:111], v[106:107], v[110:111]
	v_pk_mul_f32 v[132:133], v[132:133], v[0:1] op_sel_hi:[1,0]
	v_pk_mul_f32 v[124:125], v[124:125], v[0:1] op_sel_hi:[1,0]
	v_pk_mul_f32 v[116:117], v[116:117], v[0:1] op_sel:[0,1]
	v_pk_mul_f32 v[134:135], v[136:137], v[0:1] op_sel_hi:[1,0]
	v_exp_f32_e32 v128, v128
	v_exp_f32_e32 v129, v129
	v_pk_mul_f32 v[118:119], v[120:121], v[0:1] op_sel:[0,1]
	v_pk_mul_f32 v[106:107], v[112:113], v[0:1] op_sel:[0,1]
	v_pk_mul_f32 v[0:1], v[108:109], v[0:1] op_sel:[0,1]
	v_pk_add_f32 v[128:129], v[128:129], 1.0 op_sel_hi:[1,0]
	v_pk_mul_f32 v[108:109], v[106:107], s[22:23] op_sel_hi:[1,0]
	v_pk_mul_f32 v[214:215], v[134:135], s[22:23] op_sel_hi:[1,0]
	v_rcp_f32_e32 v128, v128
	v_rcp_f32_e32 v129, v129
	v_exp_f32_e32 v108, v108
	v_exp_f32_e32 v109, v109
	v_pk_mul_f32 v[126:127], v[126:127], v[128:129]
	v_cvt_pk_bf16_f32 v128, v122, v123
	v_exp_f32_e32 v214, v214
	v_pk_add_f32 v[108:109], v[108:109], 1.0 op_sel_hi:[1,0]
	v_pk_mul_f32 v[124:125], v[124:125], v[126:127]
	v_exp_f32_e32 v215, v215
	v_rcp_f32_e32 v108, v108
	v_rcp_f32_e32 v109, v109
	v_cvt_pk_bf16_f32 v126, v130, v131
	v_mov_b64_e32 v[122:123], s[2:3]
	v_pk_mul_f32 v[220:221], v[118:119], s[22:23] op_sel_hi:[1,0]
	v_cvt_pk_bf16_f32 v129, v124, v125
	v_mad_u64_u32 v[130:131], s[14:15], v182, s91, v[122:123]
	v_exp_f32_e32 v220, v220
	v_exp_f32_e32 v221, v221
	v_pk_mul_f32 v[106:107], v[106:107], v[108:109]
	v_pk_add_f32 v[214:215], v[214:215], 1.0 op_sel_hi:[1,0]
	v_mov_b32_e32 v124, v131
	v_pk_mul_f32 v[0:1], v[0:1], v[106:107]
	v_rcp_f32_e32 v214, v214
	v_rcp_f32_e32 v215, v215
	v_mad_u64_u32 v[124:125], s[14:15], v183, s91, v[124:125]
	v_pk_add_f32 v[220:221], v[220:221], 1.0 op_sel_hi:[1,0]
	v_cvt_pk_bf16_f32 v109, v0, v1
	v_lshl_or_b32 v142, s56, 7, v209
	v_rcp_f32_e32 v220, v220
	v_rcp_f32_e32 v221, v221
	v_cvt_pk_bf16_f32 v108, v110, v111
	v_mad_u64_u32 v[0:1], s[14:15], v180, s91, v[122:123]
	v_ashrrev_i32_e32 v143, 31, v142
	v_pk_mul_f32 v[94:95], v[94:95], v[2:3] op_sel_hi:[1,0]
	v_pk_mul_f32 v[134:135], v[134:135], v[214:215]
	v_mov_b32_e32 v131, v124
	v_mov_b32_e32 v110, v1
	v_pk_mul_f32 v[132:133], v[132:133], v[134:135]
	v_lshlrev_b64 v[124:125], 1, v[142:143]
	v_pk_mul_f32 v[118:119], v[118:119], v[220:221]
	v_mad_u64_u32 v[110:111], s[14:15], v181, s91, v[110:111]
	v_pk_mul_f32 v[228:229], v[94:95], s[22:23] op_sel_hi:[1,0]
	v_cvt_pk_bf16_f32 v127, v132, v133
	v_lshl_add_u64 v[130:131], v[130:131], 0, v[124:125]
	v_pk_mul_f32 v[116:117], v[116:117], v[118:119]
	v_mov_b32_e32 v1, v110
	v_exp_f32_e32 v228, v228
	v_exp_f32_e32 v229, v229
	global_store_dwordx4 v[130:131], v[126:129], off
	v_cvt_pk_bf16_f32 v106, v114, v115
	v_cvt_pk_bf16_f32 v107, v116, v117
	v_lshl_add_u64 v[0:1], v[0:1], 0, v[124:125]
	v_pk_add_f32 v[228:229], v[228:229], 1.0 op_sel_hi:[1,0]
	v_pk_mul_f32 v[90:91], v[90:91], v[2:3] op_sel_hi:[1,0]
	global_store_dwordx4 v[0:1], v[106:109], off
	s_nop 1
	v_pk_mul_f32 v[0:1], v[102:103], v[2:3] op_sel_hi:[1,0]
	v_rcp_f32_e32 v228, v228
	v_rcp_f32_e32 v229, v229
	v_pk_mul_f32 v[224:225], v[0:1], s[22:23] op_sel_hi:[1,0]
	v_pk_mul_f32 v[98:99], v[98:99], v[2:3] op_sel_hi:[1,0]
	v_pk_mul_f32 v[92:93], v[92:93], v[2:3] op_sel_hi:[1,0]
	v_exp_f32_e32 v224, v224
	v_exp_f32_e32 v225, v225
	v_pk_mul_f32 v[94:95], v[94:95], v[228:229]
	v_pk_mul_f32 v[100:101], v[100:101], v[2:3] op_sel_hi:[1,0]
	v_pk_mul_f32 v[62:63], v[62:63], v[4:5] op_sel_hi:[1,0]
	v_pk_mul_f32 v[94:95], v[90:91], v[94:95]
	v_pk_add_f32 v[224:225], v[224:225], 1.0 op_sel_hi:[1,0]
	v_pk_mul_f32 v[90:91], v[96:97], v[2:3] op_sel_hi:[1,0]
	v_pk_mul_f32 v[212:213], v[62:63], s[22:23] op_sel_hi:[1,0]
	v_rcp_f32_e32 v224, v224
	v_rcp_f32_e32 v225, v225
	v_pk_mul_f32 v[230:231], v[90:91], s[22:23] op_sel_hi:[1,0]
	v_exp_f32_e32 v212, v212
	v_exp_f32_e32 v230, v230
	v_exp_f32_e32 v231, v231
	v_pk_mul_f32 v[0:1], v[0:1], v[224:225]
	v_exp_f32_e32 v213, v213
	v_pk_mul_f32 v[0:1], v[98:99], v[0:1]
	v_pk_add_f32 v[230:231], v[230:231], 1.0 op_sel_hi:[1,0]
	v_pk_mul_f32 v[98:99], v[104:105], v[2:3] op_sel_hi:[1,0]
	v_pk_add_f32 v[212:213], v[212:213], 1.0 op_sel_hi:[1,0]
	v_rcp_f32_e32 v230, v230
	v_rcp_f32_e32 v231, v231
	v_pk_mul_f32 v[226:227], v[98:99], s[22:23] op_sel_hi:[1,0]
	v_rcp_f32_e32 v212, v212
	v_exp_f32_e32 v226, v226
	v_exp_f32_e32 v227, v227
	v_pk_mul_f32 v[90:91], v[90:91], v[230:231]
	v_rcp_f32_e32 v213, v213
	v_pk_mul_f32 v[96:97], v[92:93], v[90:91]
	v_pk_add_f32 v[226:227], v[226:227], 1.0 op_sel_hi:[1,0]
	v_cvt_pk_bf16_f32 v90, v0, v1
	v_mad_u64_u32 v[0:1], s[14:15], v178, s91, v[122:123]
	v_rcp_f32_e32 v226, v226
	v_rcp_f32_e32 v227, v227
	v_mov_b32_e32 v2, v1
	v_cvt_pk_bf16_f32 v92, v94, v95
	v_cvt_pk_bf16_f32 v93, v96, v97
	v_pk_mul_f32 v[98:99], v[98:99], v[226:227]
	v_mad_u64_u32 v[94:95], s[14:15], v179, s91, v[2:3]
	v_pk_mul_f32 v[58:59], v[58:59], v[4:5] op_sel_hi:[1,0]
	v_pk_mul_f32 v[98:99], v[100:101], v[98:99]
	v_mov_b32_e32 v1, v94
	v_pk_mul_f32 v[62:63], v[62:63], v[212:213]
	v_cvt_pk_bf16_f32 v91, v98, v99
	v_lshl_add_u64 v[0:1], v[0:1], 0, v[124:125]
	v_pk_mul_f32 v[58:59], v[58:59], v[62:63]
	v_pk_mul_f32 v[62:63], v[64:65], v[4:5] op_sel_hi:[1,0]
	global_store_dwordx4 v[0:1], v[90:93], off
	s_nop 1
	v_mov_b32_e32 v0, v3
	v_pk_mul_f32 v[214:215], v[62:63], s[22:23] op_sel_hi:[1,0]
	v_pk_mul_f32 v[60:61], v[60:61], v[4:5] op_sel_hi:[1,0]
	v_pk_mul_f32 v[78:79], v[78:79], v[0:1] op_sel_hi:[1,0]
	v_pk_mul_f32 v[2:3], v[86:87], v[0:1] op_sel_hi:[1,0]
	v_pk_mul_f32 v[74:75], v[74:75], v[0:1] op_sel_hi:[1,0]
	v_pk_mul_f32 v[236:237], v[78:79], s[22:23] op_sel_hi:[1,0]
	v_pk_mul_f32 v[232:233], v[2:3], s[22:23] op_sel_hi:[1,0]
	v_pk_mul_f32 v[82:83], v[82:83], v[0:1] op_sel_hi:[1,0]
	v_exp_f32_e32 v236, v236
	v_exp_f32_e32 v237, v237
	v_exp_f32_e32 v232, v232
	v_exp_f32_e32 v233, v233
	v_pk_add_f32 v[236:237], v[236:237], 1.0 op_sel_hi:[1,0]
	v_pk_mul_f32 v[84:85], v[84:85], v[0:1] op_sel_hi:[1,0]
	v_exp_f32_e32 v214, v214
	v_rcp_f32_e32 v236, v236
	v_rcp_f32_e32 v237, v237
	v_pk_add_f32 v[232:233], v[232:233], 1.0 op_sel_hi:[1,0]
	v_exp_f32_e32 v215, v215
	v_pk_mul_f32 v[78:79], v[78:79], v[236:237]
	v_rcp_f32_e32 v232, v232
	v_pk_mul_f32 v[74:75], v[74:75], v[78:79]
	v_pk_mul_f32 v[78:79], v[80:81], v[0:1] op_sel_hi:[1,0]
	v_rcp_f32_e32 v233, v233
	v_pk_mul_f32 v[238:239], v[78:79], s[22:23] op_sel_hi:[1,0]
	v_pk_add_f32 v[214:215], v[214:215], 1.0 op_sel_hi:[1,0]
	v_pk_mul_f32 v[26:27], v[26:27], v[6:7] op_sel_hi:[1,0]
	v_exp_f32_e32 v238, v238
	v_exp_f32_e32 v239, v239
	v_pk_mul_f32 v[2:3], v[2:3], v[232:233]
	v_rcp_f32_e32 v214, v214
	v_pk_mul_f32 v[2:3], v[82:83], v[2:3]
	v_pk_add_f32 v[238:239], v[238:239], 1.0 op_sel_hi:[1,0]
	v_pk_mul_f32 v[82:83], v[88:89], v[0:1] op_sel_hi:[1,0]
	v_pk_mul_f32 v[0:1], v[76:77], v[0:1] op_sel_hi:[1,0]
	v_rcp_f32_e32 v238, v238
	v_rcp_f32_e32 v239, v239
	v_pk_mul_f32 v[234:235], v[82:83], s[22:23] op_sel_hi:[1,0]
	v_rcp_f32_e32 v215, v215
	v_pk_mul_f32 v[76:77], v[78:79], v[238:239]
	v_exp_f32_e32 v234, v234
	v_exp_f32_e32 v235, v235
	v_pk_mul_f32 v[76:77], v[0:1], v[76:77]
	v_cvt_pk_bf16_f32 v0, v2, v3
	v_cvt_pk_bf16_f32 v2, v74, v75
	v_pk_add_f32 v[234:235], v[234:235], 1.0 op_sel_hi:[1,0]
	v_mad_u64_u32 v[74:75], s[14:15], v176, s91, v[122:123]
	v_cvt_pk_bf16_f32 v3, v76, v77
	v_rcp_f32_e32 v234, v234
	v_rcp_f32_e32 v235, v235
	v_mov_b32_e32 v76, v75
	v_pk_mul_f32 v[62:63], v[62:63], v[214:215]
	v_pk_mul_f32 v[28:29], v[28:29], v[6:7] op_sel_hi:[1,0]
	v_pk_mul_f32 v[82:83], v[82:83], v[234:235]
	v_mad_u64_u32 v[76:77], s[14:15], v177, s91, v[76:77]
	v_pk_mul_f32 v[60:61], v[60:61], v[62:63]
	v_pk_mul_f32 v[82:83], v[84:85], v[82:83]
	v_mov_b32_e32 v75, v76
	s_andn2_b64 vcc, exec, s[40:41]
	v_cvt_pk_bf16_f32 v1, v82, v83
	v_lshl_add_u64 v[74:75], v[74:75], 0, v[124:125]
	s_nop 0
	global_store_dwordx4 v[74:75], v[0:3], off
	s_nop 1
	v_pk_mul_f32 v[0:1], v[70:71], v[4:5] op_sel_hi:[1,0]
	v_pk_mul_f32 v[2:3], v[66:67], v[4:5] op_sel_hi:[1,0]
	v_pk_mul_f32 v[66:67], v[68:69], v[4:5] op_sel_hi:[1,0]
	v_pk_mul_f32 v[240:241], v[0:1], s[22:23] op_sel_hi:[1,0]
	s_nop 0
	v_exp_f32_e32 v240, v240
	v_exp_f32_e32 v241, v241
	s_nop 0
	v_pk_add_f32 v[240:241], v[240:241], 1.0 op_sel_hi:[1,0]
	s_nop 0
	v_rcp_f32_e32 v240, v240
	v_rcp_f32_e32 v241, v241
	s_nop 0
	v_pk_mul_f32 v[0:1], v[0:1], v[240:241]
	s_nop 0
	v_pk_mul_f32 v[0:1], v[2:3], v[0:1]
	v_pk_mul_f32 v[2:3], v[72:73], v[4:5] op_sel_hi:[1,0]
	v_cvt_pk_bf16_f32 v0, v0, v1
	v_pk_mul_f32 v[242:243], v[2:3], s[22:23] op_sel_hi:[1,0]
	s_nop 0
	v_exp_f32_e32 v242, v242
	v_exp_f32_e32 v243, v243
	s_nop 0
	v_pk_add_f32 v[242:243], v[242:243], 1.0 op_sel_hi:[1,0]
	s_nop 0
	v_rcp_f32_e32 v242, v242
	v_rcp_f32_e32 v243, v243
	s_nop 0
	v_pk_mul_f32 v[2:3], v[2:3], v[242:243]
	s_nop 0
	v_pk_mul_f32 v[2:3], v[66:67], v[2:3]
	s_nop 0
	v_cvt_pk_bf16_f32 v1, v2, v3
	v_cvt_pk_bf16_f32 v2, v58, v59
	v_mad_u64_u32 v[58:59], s[14:15], v140, s91, v[122:123]
	v_cvt_pk_bf16_f32 v3, v60, v61
	v_mov_b32_e32 v4, v59
	s_nop 0
	v_mad_u64_u32 v[60:61], s[14:15], v141, s91, v[4:5]
	s_nop 0
	v_mov_b32_e32 v59, v60
	s_nop 0
	v_lshl_add_u64 v[58:59], v[58:59], 0, v[124:125]
	s_nop 0
	global_store_dwordx4 v[58:59], v[0:3], off
	s_nop 1
	v_mov_b32_e32 v0, v5
	s_nop 0
	v_pk_mul_f32 v[2:3], v[54:55], v[0:1] op_sel_hi:[1,0]
	v_pk_mul_f32 v[46:47], v[46:47], v[0:1] op_sel_hi:[1,0]
	v_pk_mul_f32 v[4:5], v[50:51], v[0:1] op_sel_hi:[1,0]
	v_pk_mul_f32 v[216:217], v[2:3], s[22:23] op_sel_hi:[1,0]
	v_pk_mul_f32 v[220:221], v[46:47], s[22:23] op_sel_hi:[1,0]
	v_pk_mul_f32 v[42:43], v[42:43], v[0:1] op_sel_hi:[1,0]
	v_exp_f32_e32 v216, v216
	v_exp_f32_e32 v217, v217
	v_exp_f32_e32 v220, v220
	v_exp_f32_e32 v221, v221
	v_pk_add_f32 v[216:217], v[216:217], 1.0 op_sel_hi:[1,0]
	v_pk_mul_f32 v[50:51], v[52:53], v[0:1] op_sel_hi:[1,0]
	v_rcp_f32_e32 v216, v216
	v_pk_add_f32 v[220:221], v[220:221], 1.0 op_sel_hi:[1,0]
	v_rcp_f32_e32 v217, v217
	v_rcp_f32_e32 v220, v220
	v_rcp_f32_e32 v221, v221
	v_pk_mul_f32 v[2:3], v[2:3], v[216:217]
	s_nop 0
	v_pk_mul_f32 v[2:3], v[4:5], v[2:3]
	v_pk_mul_f32 v[46:47], v[46:47], v[220:221]
	v_pk_mul_f32 v[4:5], v[56:57], v[0:1] op_sel_hi:[1,0]
	v_pk_mul_f32 v[42:43], v[42:43], v[46:47]
	v_pk_mul_f32 v[46:47], v[48:49], v[0:1] op_sel_hi:[1,0]
	v_pk_mul_f32 v[218:219], v[4:5], s[22:23] op_sel_hi:[1,0]
	v_pk_mul_f32 v[0:1], v[44:45], v[0:1] op_sel_hi:[1,0]
	v_pk_mul_f32 v[222:223], v[46:47], s[22:23] op_sel_hi:[1,0]
	v_exp_f32_e32 v218, v218
	v_exp_f32_e32 v219, v219
	v_exp_f32_e32 v222, v222
	v_exp_f32_e32 v223, v223
	v_pk_add_f32 v[218:219], v[218:219], 1.0 op_sel_hi:[1,0]
	s_nop 0
	v_rcp_f32_e32 v218, v218
	v_pk_add_f32 v[222:223], v[222:223], 1.0 op_sel_hi:[1,0]
	v_rcp_f32_e32 v219, v219
	v_rcp_f32_e32 v222, v222
	v_rcp_f32_e32 v223, v223
	v_pk_mul_f32 v[4:5], v[4:5], v[218:219]
	s_nop 0
	v_pk_mul_f32 v[4:5], v[50:51], v[4:5]
	v_pk_mul_f32 v[44:45], v[46:47], v[222:223]
	v_add_u32_e32 v46, 16, v138
	v_pk_mul_f32 v[44:45], v[0:1], v[44:45]
	v_cvt_pk_bf16_f32 v1, v4, v5
	v_cvt_pk_bf16_f32 v0, v2, v3
	v_mad_i64_i32 v[4:5], s[14:15], v46, s91, v[122:123]
	v_cvt_pk_bf16_f32 v2, v42, v43
	v_cvt_pk_bf16_f32 v3, v44, v45
	v_lshl_add_u64 v[4:5], v[4:5], 0, v[124:125]
	s_nop 0
	global_store_dwordx4 v[4:5], v[0:3], off
	s_nop 1
	v_pk_mul_f32 v[0:1], v[38:39], v[6:7] op_sel_hi:[1,0]
	v_pk_mul_f32 v[2:3], v[34:35], v[6:7] op_sel_hi:[1,0]
	v_pk_mul_f32 v[4:5], v[36:37], v[6:7] op_sel_hi:[1,0]
	v_pk_mul_f32 v[224:225], v[0:1], s[22:23] op_sel_hi:[1,0]
	s_nop 0
	v_exp_f32_e32 v224, v224
	v_exp_f32_e32 v225, v225
	s_nop 0
	v_pk_add_f32 v[224:225], v[224:225], 1.0 op_sel_hi:[1,0]
	s_nop 0
	v_rcp_f32_e32 v224, v224
	v_rcp_f32_e32 v225, v225
	s_nop 0
	v_pk_mul_f32 v[0:1], v[0:1], v[224:225]
	s_nop 0
	v_pk_mul_f32 v[0:1], v[2:3], v[0:1]
	v_pk_mul_f32 v[2:3], v[40:41], v[6:7] op_sel_hi:[1,0]
	v_cvt_pk_bf16_f32 v0, v0, v1
	v_pk_mul_f32 v[226:227], v[2:3], s[22:23] op_sel_hi:[1,0]
	s_nop 0
	v_exp_f32_e32 v226, v226
	v_exp_f32_e32 v227, v227
	s_nop 0
	v_pk_add_f32 v[226:227], v[226:227], 1.0 op_sel_hi:[1,0]
	s_nop 0
	v_rcp_f32_e32 v226, v226
	v_rcp_f32_e32 v227, v227
	s_nop 0
	v_pk_mul_f32 v[2:3], v[2:3], v[226:227]
	s_nop 0
	v_pk_mul_f32 v[2:3], v[4:5], v[2:3]
	v_pk_mul_f32 v[4:5], v[30:31], v[6:7] op_sel_hi:[1,0]
	v_cvt_pk_bf16_f32 v1, v2, v3
	v_pk_mul_f32 v[228:229], v[4:5], s[22:23] op_sel_hi:[1,0]
	s_nop 0
	v_exp_f32_e32 v228, v228
	v_exp_f32_e32 v229, v229
	s_nop 0
	v_pk_add_f32 v[228:229], v[228:229], 1.0 op_sel_hi:[1,0]
	s_nop 0
	v_rcp_f32_e32 v228, v228
	v_rcp_f32_e32 v229, v229
	s_nop 0
	v_pk_mul_f32 v[4:5], v[4:5], v[228:229]
	s_nop 0
	v_pk_mul_f32 v[4:5], v[26:27], v[4:5]
	v_pk_mul_f32 v[26:27], v[32:33], v[6:7] op_sel_hi:[1,0]
	v_add_u32_e32 v6, 32, v138
	v_cvt_pk_bf16_f32 v2, v4, v5
	v_pk_mul_f32 v[230:231], v[26:27], s[22:23] op_sel_hi:[1,0]
	v_mad_i64_i32 v[4:5], s[14:15], v6, s91, v[122:123]
	v_exp_f32_e32 v230, v230
	v_exp_f32_e32 v231, v231
	v_lshl_add_u64 v[4:5], v[4:5], 0, v[124:125]
	v_pk_add_f32 v[230:231], v[230:231], 1.0 op_sel_hi:[1,0]
	s_nop 0
	v_rcp_f32_e32 v230, v230
	v_rcp_f32_e32 v231, v231
	s_nop 0
	v_pk_mul_f32 v[26:27], v[26:27], v[230:231]
	s_nop 0
	v_pk_mul_f32 v[26:27], v[28:29], v[26:27]
	s_nop 0
	v_cvt_pk_bf16_f32 v3, v26, v27
	s_nop 0
	global_store_dwordx4 v[4:5], v[0:3], off
	s_nop 1
	v_mov_b32_e32 v0, v7
	s_nop 0
	v_pk_mul_f32 v[2:3], v[22:23], v[0:1] op_sel_hi:[1,0]
	v_pk_mul_f32 v[4:5], v[16:17], v[0:1] op_sel_hi:[1,0]
	v_pk_mul_f32 v[6:7], v[18:19], v[0:1] op_sel_hi:[1,0]
	v_pk_mul_f32 v[232:233], v[2:3], s[22:23] op_sel_hi:[1,0]
	v_pk_mul_f32 v[8:9], v[8:9], v[0:1] op_sel_hi:[1,0]
	v_exp_f32_e32 v232, v232
	v_exp_f32_e32 v233, v233
	s_nop 0
	v_pk_add_f32 v[232:233], v[232:233], 1.0 op_sel_hi:[1,0]
	s_nop 0
	v_rcp_f32_e32 v232, v232
	v_rcp_f32_e32 v233, v233
	s_nop 0
	v_pk_mul_f32 v[2:3], v[2:3], v[232:233]
	s_nop 0
	v_pk_mul_f32 v[2:3], v[4:5], v[2:3]
	v_pk_mul_f32 v[4:5], v[24:25], v[0:1] op_sel_hi:[1,0]
	s_nop 0
	v_pk_mul_f32 v[234:235], v[4:5], s[22:23] op_sel_hi:[1,0]
	s_nop 0
	v_exp_f32_e32 v234, v234
	v_exp_f32_e32 v235, v235
	s_nop 0
	v_pk_add_f32 v[234:235], v[234:235], 1.0 op_sel_hi:[1,0]
	s_nop 0
	v_rcp_f32_e32 v234, v234
	v_rcp_f32_e32 v235, v235
	s_nop 0
	v_pk_mul_f32 v[4:5], v[4:5], v[234:235]
	s_nop 0
	v_pk_mul_f32 v[4:5], v[6:7], v[4:5]
	v_pk_mul_f32 v[6:7], v[12:13], v[0:1] op_sel_hi:[1,0]
	s_nop 0
	v_pk_mul_f32 v[236:237], v[6:7], s[22:23] op_sel_hi:[1,0]
	s_nop 0
	v_exp_f32_e32 v236, v236
	v_exp_f32_e32 v237, v237
	s_nop 0
	v_pk_add_f32 v[236:237], v[236:237], 1.0 op_sel_hi:[1,0]
	s_nop 0
	v_rcp_f32_e32 v236, v236
	v_rcp_f32_e32 v237, v237
	s_nop 0
	v_pk_mul_f32 v[6:7], v[6:7], v[236:237]
	s_nop 0
	v_pk_mul_f32 v[6:7], v[8:9], v[6:7]
	v_pk_mul_f32 v[8:9], v[14:15], v[0:1] op_sel_hi:[1,0]
	v_pk_mul_f32 v[0:1], v[10:11], v[0:1] op_sel_hi:[1,0]
	v_pk_mul_f32 v[10:11], v[8:9], s[22:23] op_sel_hi:[1,0]
	s_nop 0
	v_exp_f32_e32 v10, v10
	v_exp_f32_e32 v11, v11
	s_nop 0
	v_pk_add_f32 v[10:11], v[10:11], 1.0 op_sel_hi:[1,0]
	s_nop 0
	v_rcp_f32_e32 v10, v10
	v_rcp_f32_e32 v11, v11
	s_nop 0
	v_pk_mul_f32 v[8:9], v[8:9], v[10:11]
	v_add_u32_e32 v10, 48, v138
	v_pk_mul_f32 v[8:9], v[0:1], v[8:9]
	v_cvt_pk_bf16_f32 v1, v4, v5
	v_cvt_pk_bf16_f32 v0, v2, v3
	v_mad_i64_i32 v[4:5], s[14:15], v10, s91, v[122:123]
	v_cvt_pk_bf16_f32 v2, v6, v7
	v_cvt_pk_bf16_f32 v3, v8, v9
	v_lshl_add_u64 v[4:5], v[4:5], 0, v[124:125]
	s_mov_b64 s[14:15], -1
	global_store_dwordx4 v[4:5], v[0:3], off
	s_cbranch_vccnz .LBB0_1590
	s_andn2_b64 vcc, exec, s[4:5]
	s_cbranch_vccnz .LBB0_1589
	s_barrier
	s_branch .LBB0_1589
